# fox unit prologue: kmax partials and the per-thread F value requested at unit start instead of serially behind the Q pass
# speedup vs baseline: 1.0033x; 1.0033x over previous
; DI void unpack8(uint4 v, float* f) { f[0] = bflo(v.x); f[1] = bfhi(v.x); f[2] = bflo(v.y); f[3] = bfhi(v.y); f[4] = bflo(v.z); f[5] = bfhi(v.z); f[6] = bflo(v.w); f[7] = bfhi(v.w); }
; DI float shx(float v, int m, int lane) { return __int_as_float(__builtin_amdgcn_ds_bpermute((lane ^ m) << 2, __float_as_int(v))); }
; DI void fox_unit(const Params& p, int hf, int bl, int fh, int qb, unsigned char* shm, int tid, bool dry = false) {
;     ...
;   const int q0 = qb * 256, qg0 = q0 + wid * 32 + fr;
;   bf16x8 qf[2][2];
; #pragma unroll
;   for (int mi = 0; mi < 2; ++mi)
; #pragma unroll
;     for (int ks = 0; ks < 2; ++ks) {
;       const uint4 raw = *(const uint4*)(projb + (size_t)(qg0 + 16 * mi) * NP + C_FQ + fh * 64 + ks * 32 + fq * 8);
;       qf[mi][ks] = __builtin_bit_cast(bf16x8, raw);
;     }
;   float qmax2 = 0.f;
; #pragma unroll
;   for (int mi = 0; mi < 2; ++mi) {
;     float ssum = 0.f;
; #pragma unroll
;     for (int ks = 0; ks < 2; ++ks) { float f[8]; unpack8(__builtin_bit_cast(uint4, qf[mi][ks]), f);
; #pragma unroll
;       for (int z = 0; z < 8; ++z) ssum += f[z] * f[z]; }
;     ssum += shx(ssum, 16, lane); ssum += shx(ssum, 32, lane);
;     qmax2 = fmaxf(qmax2, ssum);
;   }
; #pragma unroll
;   for (int o_ = 8; o_ >= 1; o_ >>= 1) qmax2 = fmaxf(qmax2, shx(qmax2, o_, lane));
;   float* sRed = (float*)(shm + 2 * STG);
;   if (lane == 0) sRed[wid] = qmax2;
;     ...
;   const float kmax2 = ((const float*)(wsb + WS_KMAX))[bl * 8 + fh];
;   const float thr = -110.0f - 0.25f * sqrtf(qm2 * kmax2) * 1.02f;
;   const int nkt = 4 * qb + 4;
;   int skip = 0;
;   if (tid < 4 * qb) skip = (Fref - F[tid * 64 + 63] < thr) ? 1 : 0;
.LBB0_468:
	s_and_b64 vcc, exec, s[0:1]
	s_cbranch_vccz .LBB0_499
	v_readlane_b32 s0, v254, 60
	s_addk_i32 s0, 0xfec0
	s_lshr_b32 s0, s0, 4
	s_sub_i32 s4, 31, s0
	s_bfe_i32 s0, s23, 0x10003
	s_and_b32 s0, s0, 0x6800000
	v_mov_b32_e32 v205, v163
	v_readlane_b32 s100, v253, 36
	v_readlane_b32 s101, v253, 37
	s_and_b32 s98, s23, 15
	s_lshl_b32 s99, s98, 4
	v_mov_b32_e32 v45, s99
	s_nop 4
	global_load_dwordx4 v[40:43], v45, s[100:101]
	v_readlane_b32 s100, v253, 34
	v_readlane_b32 s101, v253, 35
	s_lshl_b32 s99, s98, 15
	s_add_u32 s100, s100, s99
	s_addc_u32 s101, s101, 0
	v_lshlrev_b32_e32 v46, 8, v205
	s_lshl_b32 s98, s4, 2
	v_cmp_gt_i32_e32 vcc, s98, v205
	s_mov_b64 s[98:99], exec
	s_and_b64 exec, exec, vcc
	global_load_dword v44, v46, s[100:101] offset:252
	s_mov_b64 exec, s[98:99]
	s_add_u32 s6, s38, s0
	s_addc_u32 s7, s39, 0
	v_ashrrev_i32_e32 v26, 6, v205
	s_lshl_b32 s5, s4, 8
	v_and_b32_e32 v27, 15, v205
	v_lshl_add_u32 v28, v26, 5, s5
	s_lshl_b32 s0, s23, 6
	v_or_b32_e32 v206, v28, v27
	s_and_b32 s2, s0, 0x1c0
	v_mov_b64_e32 v[8:9], s[6:7]
	v_mad_i64_i32 v[126:127], s[0:1], v206, s65, v[8:9]
	s_lshl_b32 s2, s2, 1
	v_lshl_add_u64 v[0:1], v[126:127], 0, s[2:3]
	v_and_b32_e32 v24, 48, v205
	v_mov_b32_e32 v25, v161
	v_lshl_add_u64 v[0:1], v[0:1], 0, v[24:25]
	s_mov_b64 s[10:11], 0x1800
	s_movk_i32 s8, 0x1000
	v_lshl_add_u64 v[4:5], v[0:1], 0, s[10:11]
	v_add_co_u32_e32 v0, vcc, s8, v0
	v_or_b32_e32 v207, 16, v206
	s_nop 0
	v_addc_co_u32_e32 v1, vcc, 0, v1, vcc
	global_load_dwordx4 v[0:3], v[0:1], off offset:2048
	s_nop 0
	global_load_dwordx4 v[4:7], v[4:5], off offset:64
	v_mad_i64_i32 v[108:109], s[0:1], v207, s65, v[8:9]
	v_lshl_add_u64 v[8:9], v[108:109], 0, s[2:3]
	v_lshl_add_u64 v[8:9], v[8:9], 0, v[24:25]
	v_lshl_add_u64 v[12:13], v[8:9], 0, s[10:11]
	v_add_co_u32_e32 v8, vcc, s8, v8
	v_and_b32_e32 v16, 63, v205
	s_nop 0
	v_addc_co_u32_e32 v9, vcc, 0, v9, vcc
	global_load_dwordx4 v[8:11], v[8:9], off offset:2048
	s_nop 0
	global_load_dwordx4 v[12:15], v[12:13], off offset:64
	v_lshlrev_b32_e32 v18, 2, v16
	v_xor_b32_e32 v204, 64, v18
	v_xor_b32_e32 v169, 0x80, v18
	v_cmp_eq_u32_e32 vcc, 0, v16
	v_lshl_add_u32 v16, v26, 2, 32
	s_waitcnt vmcnt(3)
	v_and_b32_e32 v19, 0xffff0000, v0
	v_lshlrev_b32_e32 v17, 16, v0
	v_mul_f32_e32 v19, v19, v19
	v_lshlrev_b32_e32 v20, 16, v1
	v_fmac_f32_e32 v19, v17, v17
	v_and_b32_e32 v21, 0xffff0000, v1
	v_fmac_f32_e32 v19, v20, v20
	v_lshlrev_b32_e32 v22, 16, v2
	v_fmac_f32_e32 v19, v21, v21
	v_and_b32_e32 v23, 0xffff0000, v2
	v_fmac_f32_e32 v19, v22, v22
	v_lshlrev_b32_e32 v25, 16, v3
	v_fmac_f32_e32 v19, v23, v23
	v_and_b32_e32 v29, 0xffff0000, v3
	v_fmac_f32_e32 v19, v25, v25
	v_fmac_f32_e32 v19, v29, v29
	s_waitcnt vmcnt(2)
	v_lshlrev_b32_e32 v17, 16, v4
	v_and_b32_e32 v20, 0xffff0000, v4
	v_fmac_f32_e32 v19, v17, v17
	v_lshlrev_b32_e32 v21, 16, v5
	v_fmac_f32_e32 v19, v20, v20
	v_and_b32_e32 v22, 0xffff0000, v5
	v_fmac_f32_e32 v19, v21, v21
	v_lshlrev_b32_e32 v23, 16, v6
	v_fmac_f32_e32 v19, v22, v22
	v_and_b32_e32 v25, 0xffff0000, v6
	v_fmac_f32_e32 v19, v23, v23
	v_lshlrev_b32_e32 v29, 16, v7
	v_fmac_f32_e32 v19, v25, v25
	v_and_b32_e32 v30, 0xffff0000, v7
	v_fmac_f32_e32 v19, v29, v29
	v_fmac_f32_e32 v19, v30, v30
	ds_bpermute_b32 v17, v204, v19
	s_waitcnt vmcnt(1)
	v_and_b32_e32 v20, 0xffff0000, v8
	v_mul_f32_e32 v20, v20, v20
	v_lshlrev_b32_e32 v21, 16, v9
	v_and_b32_e32 v22, 0xffff0000, v9
	s_waitcnt lgkmcnt(0)
	v_add_f32_e32 v17, v19, v17
	ds_bpermute_b32 v19, v169, v17
	v_lshlrev_b32_e32 v23, 16, v10
	v_and_b32_e32 v25, 0xffff0000, v10
	v_lshlrev_b32_e32 v29, 16, v11
	v_and_b32_e32 v30, 0xffff0000, v11
	s_waitcnt lgkmcnt(0)
	v_add_f32_e32 v17, v17, v19
	v_lshlrev_b32_e32 v19, 16, v8
	v_fmac_f32_e32 v20, v19, v19
	v_fmac_f32_e32 v20, v21, v21
	v_fmac_f32_e32 v20, v22, v22
	v_fmac_f32_e32 v20, v23, v23
	v_fmac_f32_e32 v20, v25, v25
	v_fmac_f32_e32 v20, v29, v29
	v_fmac_f32_e32 v20, v30, v30
	s_waitcnt vmcnt(0)
	v_lshlrev_b32_e32 v19, 16, v12
	v_and_b32_e32 v21, 0xffff0000, v12
	v_fmac_f32_e32 v20, v19, v19
	v_lshlrev_b32_e32 v22, 16, v13
	v_fmac_f32_e32 v20, v21, v21
	v_and_b32_e32 v23, 0xffff0000, v13
	v_fmac_f32_e32 v20, v22, v22
	v_lshlrev_b32_e32 v25, 16, v14
	v_fmac_f32_e32 v20, v23, v23
	v_and_b32_e32 v29, 0xffff0000, v14
	v_fmac_f32_e32 v20, v25, v25
	v_lshlrev_b32_e32 v30, 16, v15
	v_fmac_f32_e32 v20, v29, v29
	v_and_b32_e32 v31, 0xffff0000, v15
	v_fmac_f32_e32 v20, v30, v30
	v_fmac_f32_e32 v20, v31, v31
	ds_bpermute_b32 v19, v204, v20
	s_waitcnt lgkmcnt(0)
	v_add_f32_e32 v19, v20, v19
	ds_bpermute_b32 v20, v169, v19
	s_waitcnt lgkmcnt(0)
	v_add_f32_e32 v19, v19, v20
	v_max3_f32 v17, v17, 0, v19
	v_xor_b32_e32 v19, 32, v18
	ds_bpermute_b32 v19, v19, v17
	s_waitcnt lgkmcnt(0)
	v_max_f32_e32 v19, v19, v19
	v_max_f32_e32 v17, v17, v19
	v_xor_b32_e32 v19, 16, v18
	ds_bpermute_b32 v19, v19, v17
	s_waitcnt lgkmcnt(0)
	v_max_f32_e32 v19, v19, v19
	v_max_f32_e32 v17, v17, v19
	v_xor_b32_e32 v19, 8, v18
	ds_bpermute_b32 v19, v19, v17
	v_xor_b32_e32 v18, 4, v18
	s_waitcnt lgkmcnt(0)
	v_max_f32_e32 v19, v19, v19
	v_max_f32_e32 v17, v17, v19
	ds_bpermute_b32 v18, v18, v17
	s_and_saveexec_b64 s[0:1], vcc
	s_cbranch_execz .LBB0_471
	s_waitcnt lgkmcnt(0)
	v_max_f32_e32 v18, v18, v18
	v_max_f32_e32 v17, v17, v17
	v_max_f32_e32 v17, v17, v18
	ds_write_b32 v16, v17 offset:37376
; DI void fox_unit(const Params& p, int hf, int bl, int fh, int qb, unsigned char* shm, int tid, bool dry = false) {
;     ...
;   const float Fref = F[q0];
;   __syncthreads();
;   float qm2 = 0.f;
; #pragma unroll
;   for (int i = 0; i < 8; ++i) qm2 = fmaxf(qm2, sRed[i]);
;   const float kmax2 = ((const float*)(wsb + WS_KMAX))[bl * 8 + fh];
;   const float thr = -110.0f - 0.25f * sqrtf(qm2 * kmax2) * 1.02f;
;   const int nkt = 4 * qb + 4;
;   int skip = 0;
;   if (tid < 4 * qb) skip = (Fref - F[tid * 64 + 63] < thr) ? 1 : 0;
.LBB0_471:
	s_or_b64 exec, exec, s[0:1]
	s_and_b32 s12, s23, 15
	s_lshl_b32 s0, s12, 15
	v_readlane_b32 s1, v253, 34
	s_add_u32 s8, s1, s0
	v_readlane_b32 s0, v253, 35
	s_addc_u32 s9, s0, 0
	s_lshl_b32 s0, s5, 2
	v_mov_b32_e32 v17, s0
	global_load_dword v192, v17, s[8:9]
	s_lshl_b32 s17, s4, 2
	v_cmp_gt_i32_e64 s[0:1], s17, v205
	s_mov_b64 s[4:5], 0
	s_waitcnt lgkmcnt(0)
	s_barrier
	s_and_saveexec_b64 s[10:11], s[0:1]
	s_cbranch_execz .LBB0_473
	ds_read_b128 v[18:21], v203 offset:37376
	ds_read_b128 v[30:33], v203 offset:37392
	s_lshl_b32 s0, s12, 4
	s_waitcnt lgkmcnt(1)
	v_max3_f32 v17, v18, 0, v19
	v_max3_f32 v17, v17, v20, v21
	v_mov_b32_e32 v20, s0
	v_readlane_b32 s0, v253, 36
	v_readlane_b32 s1, v253, 37
	s_waitcnt lgkmcnt(0)
	v_max3_f32 v17, v17, v30, v31
	v_max3_f32 v17, v17, v32, v33
	v_lshlrev_b32_e32 v18, 6, v205
	v_ashrrev_i32_e32 v19, 31, v18
	v_lshl_add_u64 v[18:19], v[18:19], 2, s[8:9]
	s_mov_b32 s0, 0xf800000
	s_waitcnt vmcnt(0)
	v_max3_f32 v20, v40, v41, v42
	v_max_f32_e32 v20, v20, v43
	v_mul_f32_e32 v17, v17, v20
	v_cmp_gt_f32_e64 s[0:1], s0, v17
	v_mul_f32_e32 v20, 0x4f800000, v17
	s_nop 0
	v_cndmask_b32_e64 v17, v17, v20, s[0:1]
	v_sqrt_f32_e32 v20, v17
	s_nop 0
	v_add_u32_e32 v21, -1, v20
	v_fma_f32 v22, -v21, v20, v17
	v_cmp_ge_f32_e64 s[4:5], 0, v22
	v_add_u32_e32 v22, 1, v20
	s_nop 0
	v_cndmask_b32_e64 v21, v20, v21, s[4:5]
	v_fma_f32 v20, -v22, v20, v17
	v_cmp_lt_f32_e64 s[4:5], 0, v20
	s_nop 1
	v_cndmask_b32_e64 v20, v21, v22, s[4:5]
	v_mul_f32_e32 v21, 0x37800000, v20
	v_cndmask_b32_e64 v20, v20, v21, s[0:1]
	v_mov_b32_e32 v21, 0x260
	v_cmp_class_f32_e64 s[0:1], v17, v21
	s_nop 1
	v_cndmask_b32_e64 v17, v20, v17, s[0:1]
	v_mov_b32_e32 v20, v44
	v_mul_f32_e32 v17, 0x3e800000, v17
	v_mul_f32_e32 v21, 0x3f828f5c, v17
	s_waitcnt vmcnt(0)
	v_pk_add_f32 v[18:19], v[192:193], v[20:21] neg_lo:[0,1] neg_hi:[0,1]
	s_nop 0
	v_cmp_lt_f32_e64 s[0:1], v18, v19
	s_and_b64 s[4:5], s[0:1], exec

; DI void unpack8(uint4 v, float* f) { f[0] = bflo(v.x); f[1] = bfhi(v.x); f[2] = bflo(v.y); f[3] = bfhi(v.y); f[4] = bflo(v.z); f[5] = bfhi(v.z); f[6] = bflo(v.w); f[7] = bfhi(v.w); }
; DI float shx(float v, int m, int lane) { return __int_as_float(__builtin_amdgcn_ds_bpermute((lane ^ m) << 2, __float_as_int(v))); }
; DI void fox_unit(const Params& p, int hf, int bl, int fh, int qb, unsigned char* shm, int tid, bool dry = false) {
;     ...
;   const int q0 = qb * 256, qg0 = q0 + wid * 32 + fr;
;   bf16x8 qf[2][2];
; #pragma unroll
;   for (int mi = 0; mi < 2; ++mi)
; #pragma unroll
;     for (int ks = 0; ks < 2; ++ks) {
;       const uint4 raw = *(const uint4*)(projb + (size_t)(qg0 + 16 * mi) * NP + C_FQ + fh * 64 + ks * 32 + fq * 8);
;       qf[mi][ks] = __builtin_bit_cast(bf16x8, raw);
;     }
;   float qmax2 = 0.f;
; #pragma unroll
;   for (int mi = 0; mi < 2; ++mi) {
;     float ssum = 0.f;
; #pragma unroll
;     for (int ks = 0; ks < 2; ++ks) { float f[8]; unpack8(__builtin_bit_cast(uint4, qf[mi][ks]), f);
; #pragma unroll
;       for (int z = 0; z < 8; ++z) ssum += f[z] * f[z]; }
;     ssum += shx(ssum, 16, lane); ssum += shx(ssum, 32, lane);
;     qmax2 = fmaxf(qmax2, ssum);
;   }
; #pragma unroll
;   for (int o_ = 8; o_ >= 1; o_ >>= 1) qmax2 = fmaxf(qmax2, shx(qmax2, o_, lane));
;   float* sRed = (float*)(shm + 2 * STG);
;   if (lane == 0) sRed[wid] = qmax2;
;     ...
;   const float kmax2 = ((const float*)(wsb + WS_KMAX))[bl * 8 + fh];
;   const float thr = -110.0f - 0.25f * sqrtf(qm2 * kmax2) * 1.02f;
;   const int nkt = 4 * qb + 4;
;   int skip = 0;
;   if (tid < 4 * qb) skip = (Fref - F[tid * 64 + 63] < thr) ? 1 : 0;
.LBB0_588:
	s_andn2_b64 vcc, exec, s[0:1]
	s_cbranch_vccnz .LBB0_621
	v_readlane_b32 s0, v254, 60
	s_ashr_i32 s0, s0, 4
	s_sub_i32 s10, 31, s0
	s_bfe_i32 s0, s23, 0x10003
	s_and_b32 s0, s0, 0x6800000
	v_mov_b32_e32 v205, v163
	v_readlane_b32 s100, v253, 36
	v_readlane_b32 s101, v253, 37
	s_and_b32 s98, s23, 15
	s_lshl_b32 s99, s98, 4
	v_mov_b32_e32 v45, s99
	s_nop 4
	global_load_dwordx4 v[40:43], v45, s[100:101]
	v_readlane_b32 s100, v253, 34
	v_readlane_b32 s101, v253, 35
	s_lshl_b32 s99, s98, 15
	s_add_u32 s100, s100, s99
	s_addc_u32 s101, s101, 0
	v_lshlrev_b32_e32 v46, 8, v205
	s_lshl_b32 s98, s10, 2
	v_cmp_gt_i32_e32 vcc, s98, v205
	s_mov_b64 s[98:99], exec
	s_and_b64 exec, exec, vcc
	global_load_dword v44, v46, s[100:101] offset:252
	s_mov_b64 exec, s[98:99]
	s_add_u32 s6, s38, s0
	s_addc_u32 s7, s39, 0
	v_ashrrev_i32_e32 v26, 6, v205
	s_lshl_b32 s0, s10, 8
	v_and_b32_e32 v27, 15, v205
	v_lshl_add_u32 v28, v26, 5, s0
	s_lshl_b32 s1, s23, 6
	v_or_b32_e32 v206, v28, v27
	s_and_b32 s1, s1, 0x1c0
	v_mov_b64_e32 v[8:9], s[6:7]
	v_mad_i64_i32 v[126:127], s[4:5], v206, s65, v[8:9]
	s_lshl_b32 s2, s1, 1
	v_lshl_add_u64 v[0:1], v[126:127], 0, s[2:3]
	v_and_b32_e32 v24, 48, v205
	v_mov_b32_e32 v25, v161
	v_lshl_add_u64 v[0:1], v[0:1], 0, v[24:25]
	s_mov_b64 s[8:9], 0x1800
	s_movk_i32 s1, 0x1000
	v_lshl_add_u64 v[4:5], v[0:1], 0, s[8:9]
	v_add_co_u32_e32 v0, vcc, s1, v0
	v_or_b32_e32 v207, 16, v206
	s_nop 0
	v_addc_co_u32_e32 v1, vcc, 0, v1, vcc
	global_load_dwordx4 v[0:3], v[0:1], off offset:2048
	s_nop 0
	global_load_dwordx4 v[4:7], v[4:5], off offset:64
	v_mad_i64_i32 v[108:109], s[4:5], v207, s65, v[8:9]
	v_lshl_add_u64 v[8:9], v[108:109], 0, s[2:3]
	v_lshl_add_u64 v[8:9], v[8:9], 0, v[24:25]
	v_lshl_add_u64 v[12:13], v[8:9], 0, s[8:9]
	v_add_co_u32_e32 v8, vcc, s1, v8
	v_and_b32_e32 v16, 63, v205
	s_nop 0
	v_addc_co_u32_e32 v9, vcc, 0, v9, vcc
	global_load_dwordx4 v[8:11], v[8:9], off offset:2048
	s_nop 0
	global_load_dwordx4 v[12:15], v[12:13], off offset:64
	v_lshlrev_b32_e32 v18, 2, v16
	v_xor_b32_e32 v204, 64, v18
	v_xor_b32_e32 v169, 0x80, v18
	v_cmp_eq_u32_e32 vcc, 0, v16
	v_lshl_add_u32 v16, v26, 2, 32
	s_waitcnt vmcnt(3)
	v_and_b32_e32 v19, 0xffff0000, v0
	v_lshlrev_b32_e32 v17, 16, v0
	v_mul_f32_e32 v19, v19, v19
	v_lshlrev_b32_e32 v20, 16, v1
	v_fmac_f32_e32 v19, v17, v17
	v_and_b32_e32 v21, 0xffff0000, v1
	v_fmac_f32_e32 v19, v20, v20
	v_lshlrev_b32_e32 v22, 16, v2
	v_fmac_f32_e32 v19, v21, v21
	v_and_b32_e32 v23, 0xffff0000, v2
	v_fmac_f32_e32 v19, v22, v22
	v_lshlrev_b32_e32 v25, 16, v3
	v_fmac_f32_e32 v19, v23, v23
	v_and_b32_e32 v29, 0xffff0000, v3
	v_fmac_f32_e32 v19, v25, v25
	v_fmac_f32_e32 v19, v29, v29
	s_waitcnt vmcnt(2)
	v_lshlrev_b32_e32 v17, 16, v4
	v_and_b32_e32 v20, 0xffff0000, v4
	v_fmac_f32_e32 v19, v17, v17
	v_lshlrev_b32_e32 v21, 16, v5
	v_fmac_f32_e32 v19, v20, v20
	v_and_b32_e32 v22, 0xffff0000, v5
	v_fmac_f32_e32 v19, v21, v21
	v_lshlrev_b32_e32 v23, 16, v6
	v_fmac_f32_e32 v19, v22, v22
	v_and_b32_e32 v25, 0xffff0000, v6
	v_fmac_f32_e32 v19, v23, v23
	v_lshlrev_b32_e32 v29, 16, v7
	v_fmac_f32_e32 v19, v25, v25
	v_and_b32_e32 v30, 0xffff0000, v7
	v_fmac_f32_e32 v19, v29, v29
	v_fmac_f32_e32 v19, v30, v30
	ds_bpermute_b32 v17, v204, v19
	s_waitcnt vmcnt(1)
	v_and_b32_e32 v20, 0xffff0000, v8
	v_mul_f32_e32 v20, v20, v20
	v_lshlrev_b32_e32 v21, 16, v9
	v_and_b32_e32 v22, 0xffff0000, v9
	s_waitcnt lgkmcnt(0)
	v_add_f32_e32 v17, v19, v17
	ds_bpermute_b32 v19, v169, v17
	v_lshlrev_b32_e32 v23, 16, v10
	v_and_b32_e32 v25, 0xffff0000, v10
	v_lshlrev_b32_e32 v29, 16, v11
	v_and_b32_e32 v30, 0xffff0000, v11
	s_waitcnt lgkmcnt(0)
	v_add_f32_e32 v17, v17, v19
	v_lshlrev_b32_e32 v19, 16, v8
	v_fmac_f32_e32 v20, v19, v19
	v_fmac_f32_e32 v20, v21, v21
	v_fmac_f32_e32 v20, v22, v22
	v_fmac_f32_e32 v20, v23, v23
	v_fmac_f32_e32 v20, v25, v25
	v_fmac_f32_e32 v20, v29, v29
	v_fmac_f32_e32 v20, v30, v30
	s_waitcnt vmcnt(0)
	v_lshlrev_b32_e32 v19, 16, v12
	v_and_b32_e32 v21, 0xffff0000, v12
	v_fmac_f32_e32 v20, v19, v19
	v_lshlrev_b32_e32 v22, 16, v13
	v_fmac_f32_e32 v20, v21, v21
	v_and_b32_e32 v23, 0xffff0000, v13
	v_fmac_f32_e32 v20, v22, v22
	v_lshlrev_b32_e32 v25, 16, v14
	v_fmac_f32_e32 v20, v23, v23
	v_and_b32_e32 v29, 0xffff0000, v14
	v_fmac_f32_e32 v20, v25, v25
	v_lshlrev_b32_e32 v30, 16, v15
	v_fmac_f32_e32 v20, v29, v29
	v_and_b32_e32 v31, 0xffff0000, v15
	v_fmac_f32_e32 v20, v30, v30
	v_fmac_f32_e32 v20, v31, v31
	ds_bpermute_b32 v19, v204, v20
	s_waitcnt lgkmcnt(0)
	v_add_f32_e32 v19, v20, v19
	ds_bpermute_b32 v20, v169, v19
	s_waitcnt lgkmcnt(0)
	v_add_f32_e32 v19, v19, v20
	v_max3_f32 v17, v17, 0, v19
	v_xor_b32_e32 v19, 32, v18
	ds_bpermute_b32 v19, v19, v17
	s_waitcnt lgkmcnt(0)
	v_max_f32_e32 v19, v19, v19
	v_max_f32_e32 v17, v17, v19
	v_xor_b32_e32 v19, 16, v18
	ds_bpermute_b32 v19, v19, v17
	s_waitcnt lgkmcnt(0)
	v_max_f32_e32 v19, v19, v19
	v_max_f32_e32 v17, v17, v19
	v_xor_b32_e32 v19, 8, v18
	ds_bpermute_b32 v19, v19, v17
	v_xor_b32_e32 v18, 4, v18
	s_waitcnt lgkmcnt(0)
	v_max_f32_e32 v19, v19, v19
	v_max_f32_e32 v17, v17, v19
	ds_bpermute_b32 v18, v18, v17
	s_and_saveexec_b64 s[4:5], vcc
	s_cbranch_execz .LBB0_591
	s_waitcnt lgkmcnt(0)
	v_max_f32_e32 v18, v18, v18
	v_max_f32_e32 v17, v17, v17
	v_max_f32_e32 v17, v17, v18
	ds_write_b32 v16, v17 offset:37376
; DI void fox_unit(const Params& p, int hf, int bl, int fh, int qb, unsigned char* shm, int tid, bool dry = false) {
;     ...
;   const float Fref = F[q0];
;   __syncthreads();
;   float qm2 = 0.f;
; #pragma unroll
;   for (int i = 0; i < 8; ++i) qm2 = fmaxf(qm2, sRed[i]);
;   const float kmax2 = ((const float*)(wsb + WS_KMAX))[bl * 8 + fh];
;   const float thr = -110.0f - 0.25f * sqrtf(qm2 * kmax2) * 1.02f;
;   const int nkt = 4 * qb + 4;
;   int skip = 0;
;   if (tid < 4 * qb) skip = (Fref - F[tid * 64 + 63] < thr) ? 1 : 0;
.LBB0_591:
	s_or_b64 exec, exec, s[4:5]
	s_and_b32 s12, s23, 15
	s_lshl_b32 s1, s12, 15
	v_readlane_b32 s4, v253, 34
	s_add_u32 s8, s4, s1
	v_readlane_b32 s1, v253, 35
	s_addc_u32 s9, s1, 0
	s_mov_b32 s1, s3
	s_lshl_b64 s[0:1], s[0:1], 2
	s_add_u32 s0, s8, s0
	s_addc_u32 s1, s9, s1
	global_load_dword v192, v161, s[0:1]
	s_lshl_b32 s16, s10, 2
	v_cmp_gt_i32_e64 s[0:1], s16, v205
	s_mov_b64 s[4:5], 0
	s_waitcnt lgkmcnt(0)
	s_barrier
	s_and_saveexec_b64 s[10:11], s[0:1]
	s_cbranch_execz .LBB0_593
	ds_read_b128 v[18:21], v203 offset:37376
	ds_read_b128 v[30:33], v203 offset:37392
	s_lshl_b32 s0, s12, 4
	s_waitcnt lgkmcnt(1)
	v_max3_f32 v17, v18, 0, v19
	v_max3_f32 v17, v17, v20, v21
	v_mov_b32_e32 v20, s0
	v_readlane_b32 s0, v253, 36
	v_readlane_b32 s1, v253, 37
	s_waitcnt lgkmcnt(0)
	v_max3_f32 v17, v17, v30, v31
	v_max3_f32 v17, v17, v32, v33
	v_lshlrev_b32_e32 v18, 6, v205
	v_ashrrev_i32_e32 v19, 31, v18
	v_lshl_add_u64 v[18:19], v[18:19], 2, s[8:9]
	s_mov_b32 s0, 0xf800000
	s_waitcnt vmcnt(0)
	v_max3_f32 v20, v40, v41, v42
	v_max_f32_e32 v20, v20, v43
	v_mul_f32_e32 v17, v17, v20
	v_cmp_gt_f32_e64 s[0:1], s0, v17
	v_mul_f32_e32 v20, 0x4f800000, v17
	s_nop 0
	v_cndmask_b32_e64 v17, v17, v20, s[0:1]
	v_sqrt_f32_e32 v20, v17
	s_nop 0
	v_add_u32_e32 v21, -1, v20
	v_fma_f32 v22, -v21, v20, v17
	v_cmp_ge_f32_e64 s[4:5], 0, v22
	v_add_u32_e32 v22, 1, v20
	s_nop 0
	v_cndmask_b32_e64 v21, v20, v21, s[4:5]
	v_fma_f32 v20, -v22, v20, v17
	v_cmp_lt_f32_e64 s[4:5], 0, v20
	s_nop 1
	v_cndmask_b32_e64 v20, v21, v22, s[4:5]
	v_mul_f32_e32 v21, 0x37800000, v20
	v_cndmask_b32_e64 v20, v20, v21, s[0:1]
	v_mov_b32_e32 v21, 0x260
	v_cmp_class_f32_e64 s[0:1], v17, v21
	s_nop 1
	v_cndmask_b32_e64 v17, v20, v17, s[0:1]
	v_mov_b32_e32 v20, v44
	v_mul_f32_e32 v17, 0x3e800000, v17
	v_mul_f32_e32 v21, 0x3f828f5c, v17
	s_waitcnt vmcnt(0)
	v_pk_add_f32 v[18:19], v[192:193], v[20:21] neg_lo:[0,1] neg_hi:[0,1]
	s_nop 0
	v_cmp_lt_f32_e64 s[0:1], v18, v19
	s_and_b64 s[4:5], s[0:1], exec
